# rwkv_final loop: the vmcnt(0) right behind the next-iteration loads replaced by counted waits in front of each group's first use; drain before the stores
# baseline (speedup 1.0000x reference)
.LBB0_33:
	s_or_b32 s1, s20, 7
	s_mul_hi_i32 s3, s1, 0x1d00
	s_mulk_i32 s1, 0x1d00
	s_add_u32 s2, s18, s1
	s_addc_u32 s3, s19, s3
	v_lshlrev_b64 v[0:1], 1, v[160:161]
	v_lshl_add_u64 v[4:5], s[2:3], 0, v[0:1]
	s_ashr_i32 s1, s88, 7
	v_ashrrev_i32_e32 v11, 6, v160
	v_add_co_u32_e32 v6, vcc, s33, v4
	s_and_b32 s1, s1, -4
	s_nop 0
	v_addc_co_u32_e32 v7, vcc, 0, v5, vcc
	global_load_ushort v12, v[4:5], off offset:3072
	global_load_ushort v13, v[6:7], off offset:2816
	global_load_ushort v14, v[6:7], off offset:2048
	v_add_u32_e32 v4, s1, v11
	v_ashrrev_i32_e32 v5, 31, v4
	v_lshlrev_b64 v[6:7], 12, v[4:5]
	v_or_b32_e32 v6, s0, v6
	s_or_b32 s0, s20, 6
	s_mul_hi_i32 s1, s0, 0x1d00
	s_mulk_i32 s0, 0x1d00
	s_add_u32 s0, s18, s0
	v_and_b32_e32 v2, 63, v160
	v_or_b32_e32 v16, 7, v6
	v_mov_b32_e32 v17, v7
	v_readlane_b32 s60, v254, 44
	s_addc_u32 s1, s19, s1
	v_lshl_add_u64 v[4:5], v[16:17], 4, s[92:93]
	v_lshlrev_b32_e32 v2, 2, v2
	v_readlane_b32 s74, v254, 58
	v_readlane_b32 s75, v254, 59
	v_lshl_add_u64 v[18:19], s[0:1], 0, v[0:1]
	global_load_dword v15, v[4:5], off offset:8
	v_lshl_add_u64 v[4:5], s[74:75], 0, v[2:3]
	v_lshlrev_b64 v[16:17], 8, v[16:17]
	v_add_co_u32_e32 v22, vcc, s33, v18
	v_lshl_add_u64 v[16:17], v[4:5], 0, v[16:17]
	s_nop 0
	v_addc_co_u32_e32 v23, vcc, 0, v19, vcc
	s_or_b32 s0, s20, 5
	global_load_dword v16, v[16:17], off
	s_nop 0
	global_load_ushort v20, v[18:19], off offset:3072
	global_load_ushort v21, v[22:23], off offset:2816
	s_nop 0
	global_load_ushort v23, v[22:23], off offset:2048
	v_or_b32_e32 v18, 6, v6
	v_mov_b32_e32 v19, v7
	s_mul_hi_i32 s1, s0, 0x1d00
	s_mulk_i32 s0, 0x1d00
	v_lshl_add_u64 v[24:25], v[18:19], 4, s[92:93]
	v_lshlrev_b64 v[18:19], 8, v[18:19]
	s_add_u32 s0, s18, s0
	v_lshl_add_u64 v[18:19], v[4:5], 0, v[18:19]
	s_addc_u32 s1, s19, s1
	global_load_dword v27, v[18:19], off
	v_lshl_add_u64 v[18:19], s[0:1], 0, v[0:1]
	v_add_co_u32_e32 v28, vcc, s33, v18
	s_or_b32 s0, s20, 4
	global_load_dword v24, v[24:25], off offset:8
	v_addc_co_u32_e32 v29, vcc, 0, v19, vcc
	global_load_ushort v36, v[18:19], off offset:3072
	global_load_ushort v48, v[28:29], off offset:2816
	global_load_ushort v57, v[28:29], off offset:2048
	v_or_b32_e32 v18, 5, v6
	v_mov_b32_e32 v19, v7
	s_mul_hi_i32 s1, s0, 0x1d00
	s_mulk_i32 s0, 0x1d00
	v_lshl_add_u64 v[28:29], v[18:19], 4, s[92:93]
	v_lshlrev_b64 v[18:19], 8, v[18:19]
	s_add_u32 s0, s18, s0
	v_lshl_add_u64 v[18:19], v[4:5], 0, v[18:19]
	s_addc_u32 s1, s19, s1
	global_load_dword v65, v[18:19], off
	v_lshl_add_u64 v[18:19], s[0:1], 0, v[0:1]
	global_load_dword v60, v[28:29], off offset:8
	v_add_co_u32_e32 v28, vcc, s33, v18
	s_or_b32 s0, s20, 3
	s_nop 0
	v_addc_co_u32_e32 v29, vcc, 0, v19, vcc
	global_load_ushort v71, v[18:19], off offset:3072
	global_load_ushort v72, v[28:29], off offset:2816
	global_load_ushort v73, v[28:29], off offset:2048
	v_or_b32_e32 v18, 4, v6
	v_mov_b32_e32 v19, v7
	s_mul_hi_i32 s1, s0, 0x1d00
	s_mulk_i32 s0, 0x1d00
	v_lshl_add_u64 v[28:29], v[18:19], 4, s[92:93]
	v_lshlrev_b64 v[18:19], 8, v[18:19]
	s_add_u32 s0, s18, s0
	v_lshl_add_u64 v[18:19], v[4:5], 0, v[18:19]
	s_addc_u32 s1, s19, s1
	global_load_dword v75, v[18:19], off
	v_lshl_add_u64 v[18:19], s[0:1], 0, v[0:1]
	global_load_dword v74, v[28:29], off offset:8
	v_add_co_u32_e32 v28, vcc, s33, v18
	s_or_b32 s0, s20, 2
	s_nop 0
	v_addc_co_u32_e32 v29, vcc, 0, v19, vcc
	global_load_ushort v76, v[18:19], off offset:3072
	global_load_ushort v77, v[28:29], off offset:2816
	global_load_ushort v78, v[28:29], off offset:2048
	v_or_b32_e32 v18, 3, v6
	v_mov_b32_e32 v19, v7
	s_mul_hi_i32 s1, s0, 0x1d00
	s_mulk_i32 s0, 0x1d00
	v_lshl_add_u64 v[28:29], v[18:19], 4, s[92:93]
	v_lshlrev_b64 v[18:19], 8, v[18:19]
	s_add_u32 s0, s18, s0
	v_lshl_add_u64 v[18:19], v[4:5], 0, v[18:19]
	s_addc_u32 s1, s19, s1
	global_load_dword v80, v[18:19], off
	v_lshl_add_u64 v[18:19], s[0:1], 0, v[0:1]
	global_load_dword v79, v[28:29], off offset:8
	v_add_co_u32_e32 v28, vcc, s33, v18
	s_or_b32 s0, s20, 1
	s_nop 0
	v_addc_co_u32_e32 v29, vcc, 0, v19, vcc
	global_load_ushort v81, v[18:19], off offset:3072
	global_load_ushort v82, v[28:29], off offset:2816
	global_load_ushort v83, v[28:29], off offset:2048
	v_or_b32_e32 v18, 2, v6
	v_mov_b32_e32 v19, v7
	s_mul_hi_i32 s1, s0, 0x1d00
	s_mulk_i32 s0, 0x1d00
	v_lshl_add_u64 v[28:29], v[18:19], 4, s[92:93]
	v_lshlrev_b64 v[18:19], 8, v[18:19]
	s_add_u32 s0, s18, s0
	v_lshl_add_u64 v[18:19], v[4:5], 0, v[18:19]
	s_addc_u32 s1, s19, s1
	global_load_dword v85, v[18:19], off
	v_lshl_add_u64 v[18:19], s[0:1], 0, v[0:1]
	global_load_dword v84, v[28:29], off offset:8
	v_add_co_u32_e32 v28, vcc, s33, v18
	s_mul_i32 s0, s20, 0x1d00
	s_nop 0
	v_addc_co_u32_e32 v29, vcc, 0, v19, vcc
	global_load_ushort v86, v[18:19], off offset:3072
	global_load_ushort v88, v[28:29], off offset:2816
	global_load_ushort v89, v[28:29], off offset:2048
	v_or_b32_e32 v18, 1, v6
	v_mov_b32_e32 v19, v7
	v_lshl_add_u64 v[28:29], v[18:19], 4, s[92:93]
	v_lshlrev_b64 v[18:19], 8, v[18:19]
	s_mul_hi_i32 s1, s20, 0x1d00
	s_add_u32 s0, s18, s0
	v_lshl_add_u64 v[18:19], v[4:5], 0, v[18:19]
	s_addc_u32 s1, s19, s1
	global_load_dword v91, v[18:19], off
	v_lshl_add_u64 v[18:19], s[0:1], 0, v[0:1]
	global_load_dword v90, v[28:29], off offset:8
	v_add_co_u32_e32 v28, vcc, s33, v18
	v_readlane_b32 s0, v253, 39
	s_nop 0
	v_addc_co_u32_e32 v29, vcc, 0, v19, vcc
	global_load_ushort v92, v[18:19], off offset:3072
	global_load_ushort v93, v[28:29], off offset:2816
	global_load_ushort v94, v[28:29], off offset:2048
	v_lshl_add_u64 v[18:19], v[6:7], 4, s[92:93]
	v_lshlrev_b64 v[6:7], 8, v[6:7]
	v_lshl_add_u64 v[6:7], v[4:5], 0, v[6:7]
	global_load_dword v95, v[18:19], off offset:8
	global_load_dword v96, v[6:7], off
	v_readlane_b32 s1, v253, 40
	s_load_dword s21, s[0:1], 0x0
	v_add_u32_e32 v6, 0x100, v160
	v_lshlrev_b32_e32 v2, 4, v160
	v_ashrrev_i32_e32 v18, 6, v6
	v_readlane_b32 s62, v254, 46
	v_readlane_b32 s63, v254, 47
	v_and_b32_e32 v2, 0x3f0, v2
	v_lshlrev_b32_e32 v19, 10, v11
	v_lshlrev_b32_e32 v22, 10, v18
	v_lshlrev_b32_e32 v17, 1, v160
	v_lshl_add_u64 v[6:7], s[62:63], 0, v[2:3]
	s_waitcnt lgkmcnt(0)
	s_lshl_b32 s24, s21, 3
	v_add_u32_e32 v19, v2, v19
	v_add_u32_e32 v2, v2, v22
	s_mov_b32 s38, s88
	v_readlane_b32 s61, v254, 45
	v_readlane_b32 s64, v254, 48
	v_readlane_b32 s65, v254, 49
	v_readlane_b32 s66, v254, 50
	v_readlane_b32 s67, v254, 51
	v_readlane_b32 s68, v254, 52
	v_readlane_b32 s69, v254, 53
	v_readlane_b32 s70, v254, 54
	v_readlane_b32 s71, v254, 55
	v_readlane_b32 s72, v254, 56
	v_readlane_b32 s73, v254, 57
	s_waitcnt vmcnt(0)
	s_branch .LBB0_37

.LBB0_36:
	v_add_f32_dpp v97, v96, v96 quad_perm:[1,0,3,2] row_mask:0xf bank_mask:0xf bound_ctrl:1
	v_mov_b32_e32 v98, v3
	v_lshlrev_b32_e32 v94, 16, v94
	v_add_f32_dpp v97, v97, v97 quad_perm:[2,3,0,1] row_mask:0xf bank_mask:0xf bound_ctrl:1
	v_lshlrev_b32_e32 v87, 16, v87
	v_sub_f32_e32 v87, v87, v94
	v_add_f32_dpp v97, v97, v97 row_ror:4 row_mask:0xf bank_mask:0xf bound_ctrl:1
	v_fma_f32 v87, v10, v87, v94
	v_lshlrev_b32_e32 v89, 16, v89
	v_add_f32_dpp v97, v97, v97 row_ror:8 row_mask:0xf bank_mask:0xf bound_ctrl:1
	v_lshlrev_b32_e32 v88, 16, v88
	v_lshlrev_b32_e32 v83, 16, v83
	v_mov_b32_dpp v98, v97 row_bcast:15 row_mask:0xa bank_mask:0xf bound_ctrl:1
	v_add_f32_e32 v97, v97, v98
	v_mov_b32_e32 v98, v3
	v_lshlrev_b32_e32 v82, 16, v82
	v_lshlrev_b32_e32 v78, 16, v78
	v_mov_b32_dpp v98, v97 row_bcast:31 row_mask:0xc bank_mask:0xf bound_ctrl:1
	v_add_f32_e32 v97, v97, v98
	v_mov_b32_e32 v98, v3
	v_readlane_b32 s2, v97, 63
	v_lshlrev_b32_e32 v77, 16, v77
	v_lshlrev_b32_e32 v73, 16, v73
	v_fmac_f32_e32 v96, s2, v186
	v_mul_f32_e32 v97, v96, v96
	v_lshlrev_b32_e32 v72, 16, v72
	v_lshlrev_b32_e32 v57, 16, v57
	v_mov_b32_dpp v97, v97 quad_perm:[1,0,3,2] row_mask:0xf bank_mask:0xf bound_ctrl:1
	v_fmac_f32_e32 v97, v96, v96
	v_lshlrev_b32_e32 v48, 16, v48
	v_lshlrev_b32_e32 v23, 16, v23
	v_add_f32_dpp v97, v97, v97 quad_perm:[2,3,0,1] row_mask:0xf bank_mask:0xf bound_ctrl:1
	v_lshlrev_b32_e32 v21, 16, v21
	v_lshlrev_b32_e32 v14, 16, v14
	v_add_f32_dpp v97, v97, v97 row_ror:4 row_mask:0xf bank_mask:0xf bound_ctrl:1
	v_lshlrev_b32_e32 v13, 16, v13
	s_nop 0
	v_add_f32_dpp v97, v97, v97 row_ror:8 row_mask:0xf bank_mask:0xf bound_ctrl:1
	s_nop 1
	v_mov_b32_dpp v98, v97 row_bcast:15 row_mask:0xa bank_mask:0xf bound_ctrl:1
	v_add_f32_e32 v97, v97, v98
	v_mov_b32_e32 v98, v3
	s_nop 1
	v_mov_b32_dpp v98, v97 row_bcast:31 row_mask:0xc bank_mask:0xf bound_ctrl:1
	v_add_f32_e32 v97, v97, v98
	s_nop 0
	v_readlane_b32 s2, v97, 63
	s_nop 1
	v_fma_f32 v97, s2, v187, v182
	v_cmp_gt_f32_e32 vcc, s50, v97
	v_mul_f32_e32 v98, 0x4b800000, v97
	s_nop 0
	v_cndmask_b32_e32 v97, v97, v98, vcc
	v_rsq_f32_e32 v97, v97
	s_nop 0
	v_mul_f32_e32 v98, 0x45800000, v97
	v_cndmask_b32_e32 v97, v97, v98, vcc
	v_mul_f32_e32 v96, v96, v97
	v_fma_f32 v96, v8, v96, v9
	v_fmac_f32_e32 v96, v87, v95
	v_lshlrev_b32_e32 v87, 16, v93
	v_mul_f32_e32 v93, 0xbfb8aa3b, v87
	v_exp_f32_e32 v93, v93
	s_nop 0
	v_add_f32_e32 v93, 1.0, v93
	v_div_scale_f32 v95, s[2:3], v93, v93, v87
	v_rcp_f32_e32 v97, v95
	s_nop 0
	v_fma_f32 v98, -v95, v97, 1.0
	v_fmac_f32_e32 v97, v98, v97
	v_div_scale_f32 v98, vcc, v87, v93, v87
	v_mul_f32_e32 v99, v98, v97
	v_fma_f32 v100, -v95, v99, v98
	v_fmac_f32_e32 v99, v100, v97
	v_fma_f32 v95, -v95, v99, v98
	v_div_fmas_f32 v95, v95, v97, v99
	v_div_fixup_f32 v87, v95, v93, v87
	v_mul_f32_e32 v87, v87, v96
	v_cvt_pk_bf16_f32 v87, v87, s0
	ds_write_b16 v17, v87 offset:512
	ds_write_b16 v17, v92
	v_add_f32_dpp v87, v91, v91 quad_perm:[1,0,3,2] row_mask:0xf bank_mask:0xf bound_ctrl:1
	v_mov_b32_e32 v92, v3
	s_waitcnt vmcnt(39)
	v_mov_b32_e32 v96, v25
	v_add_f32_dpp v87, v87, v87 quad_perm:[2,3,0,1] row_mask:0xf bank_mask:0xf bound_ctrl:1
	s_nop 1
	v_add_f32_dpp v87, v87, v87 row_ror:4 row_mask:0xf bank_mask:0xf bound_ctrl:1
	s_nop 1
	v_add_f32_dpp v87, v87, v87 row_ror:8 row_mask:0xf bank_mask:0xf bound_ctrl:1
	s_nop 1
	v_mov_b32_dpp v92, v87 row_bcast:15 row_mask:0xa bank_mask:0xf bound_ctrl:1
	v_add_f32_e32 v87, v87, v92
	v_mov_b32_e32 v92, v3
	s_nop 1
	v_mov_b32_dpp v92, v87 row_bcast:31 row_mask:0xc bank_mask:0xf bound_ctrl:1
	v_add_f32_e32 v87, v87, v92
	v_mov_b32_e32 v92, v3
	v_readlane_b32 s2, v87, 63
	s_nop 1
	v_fmac_f32_e32 v91, s2, v186
	v_mul_f32_e32 v87, v91, v91
	s_nop 1
	v_mov_b32_dpp v87, v87 quad_perm:[1,0,3,2] row_mask:0xf bank_mask:0xf bound_ctrl:1
	v_fmac_f32_e32 v87, v91, v91
	s_nop 1
	v_add_f32_dpp v87, v87, v87 quad_perm:[2,3,0,1] row_mask:0xf bank_mask:0xf bound_ctrl:1
	s_nop 1
	v_add_f32_dpp v87, v87, v87 row_ror:4 row_mask:0xf bank_mask:0xf bound_ctrl:1
	s_nop 1
	v_add_f32_dpp v87, v87, v87 row_ror:8 row_mask:0xf bank_mask:0xf bound_ctrl:1
	s_nop 1
	v_mov_b32_dpp v92, v87 row_bcast:15 row_mask:0xa bank_mask:0xf bound_ctrl:1
	v_add_f32_e32 v87, v87, v92
	v_mov_b32_e32 v92, v3
	s_nop 1
	v_mov_b32_dpp v92, v87 row_bcast:31 row_mask:0xc bank_mask:0xf bound_ctrl:1
	v_add_f32_e32 v87, v87, v92
	s_nop 0
	v_readlane_b32 s2, v87, 63
	s_nop 1
	v_fma_f32 v87, s2, v187, v182
	v_cmp_gt_f32_e32 vcc, s50, v87
	v_mul_f32_e32 v92, 0x4b800000, v87
	s_nop 0
	v_cndmask_b32_e32 v87, v87, v92, vcc
	v_rsq_f32_e32 v87, v87
	s_nop 0
	v_mul_f32_e32 v92, 0x45800000, v87
	v_cndmask_b32_e32 v87, v87, v92, vcc
	v_mul_f32_e32 v87, v91, v87
	v_sub_f32_e32 v91, v94, v89
	v_fma_f32 v87, v8, v87, v9
	v_fma_f32 v91, v10, v91, v89
	v_fmac_f32_e32 v87, v91, v90
	v_mul_f32_e32 v90, 0xbfb8aa3b, v88
	v_exp_f32_e32 v90, v90
	s_nop 0
	v_add_f32_e32 v90, 1.0, v90
	v_div_scale_f32 v91, s[2:3], v90, v90, v88
	v_rcp_f32_e32 v92, v91
	s_nop 0
	v_fma_f32 v93, -v91, v92, 1.0
	v_fmac_f32_e32 v92, v93, v92
	v_div_scale_f32 v93, vcc, v88, v90, v88
	v_mul_f32_e32 v94, v93, v92
	v_fma_f32 v95, -v91, v94, v93
	v_fmac_f32_e32 v94, v95, v92
	v_fma_f32 v91, -v91, v94, v93
	v_div_fmas_f32 v91, v91, v92, v94
	v_div_fixup_f32 v88, v91, v90, v88
	v_mul_f32_e32 v87, v88, v87
	v_cvt_pk_bf16_f32 v87, v87, s0
	ds_write_b16 v17, v87 offset:1536
	ds_write_b16 v17, v86 offset:1024
	v_add_f32_dpp v86, v85, v85 quad_perm:[1,0,3,2] row_mask:0xf bank_mask:0xf bound_ctrl:1
	v_mov_b32_e32 v87, v3
	s_waitcnt vmcnt(35)
	v_mov_b32_e32 v92, v33
	v_add_f32_dpp v86, v86, v86 quad_perm:[2,3,0,1] row_mask:0xf bank_mask:0xf bound_ctrl:1
	v_mov_b32_e32 v93, v31
	v_mov_b32_e32 v94, v29
	v_add_f32_dpp v86, v86, v86 row_ror:4 row_mask:0xf bank_mask:0xf bound_ctrl:1
	v_mov_b32_e32 v95, v26
	s_waitcnt vmcnt(34)
	v_mov_b32_e32 v91, v28
	v_add_f32_dpp v86, v86, v86 row_ror:8 row_mask:0xf bank_mask:0xf bound_ctrl:1
	s_nop 1
	v_mov_b32_dpp v87, v86 row_bcast:15 row_mask:0xa bank_mask:0xf bound_ctrl:1
	v_add_f32_e32 v86, v86, v87
	v_mov_b32_e32 v87, v3
	s_nop 1
	v_mov_b32_dpp v87, v86 row_bcast:31 row_mask:0xc bank_mask:0xf bound_ctrl:1
	v_add_f32_e32 v86, v86, v87
	v_mov_b32_e32 v87, v3
	v_readlane_b32 s2, v86, 63
	s_nop 1
	v_fmac_f32_e32 v85, s2, v186
	v_mul_f32_e32 v86, v85, v85
	s_nop 1
	v_mov_b32_dpp v86, v86 quad_perm:[1,0,3,2] row_mask:0xf bank_mask:0xf bound_ctrl:1
	v_fmac_f32_e32 v86, v85, v85
	s_nop 1
	v_add_f32_dpp v86, v86, v86 quad_perm:[2,3,0,1] row_mask:0xf bank_mask:0xf bound_ctrl:1
	s_nop 1
	v_add_f32_dpp v86, v86, v86 row_ror:4 row_mask:0xf bank_mask:0xf bound_ctrl:1
	s_nop 1
	v_add_f32_dpp v86, v86, v86 row_ror:8 row_mask:0xf bank_mask:0xf bound_ctrl:1
	s_nop 1
	v_mov_b32_dpp v87, v86 row_bcast:15 row_mask:0xa bank_mask:0xf bound_ctrl:1
	v_add_f32_e32 v86, v86, v87
	v_mov_b32_e32 v87, v3
	s_nop 1
	v_mov_b32_dpp v87, v86 row_bcast:31 row_mask:0xc bank_mask:0xf bound_ctrl:1
	v_add_f32_e32 v86, v86, v87
	s_nop 0
	v_readlane_b32 s2, v86, 63
	s_nop 1
	v_fma_f32 v86, s2, v187, v182
	v_cmp_gt_f32_e32 vcc, s50, v86
	v_mul_f32_e32 v87, 0x4b800000, v86
	s_nop 0
	v_cndmask_b32_e32 v86, v86, v87, vcc
	v_rsq_f32_e32 v86, v86
	s_nop 0
	v_mul_f32_e32 v87, 0x45800000, v86
	v_cndmask_b32_e32 v86, v86, v87, vcc
	v_mul_f32_e32 v85, v85, v86
	v_sub_f32_e32 v86, v89, v83
	v_fma_f32 v85, v8, v85, v9
	v_fma_f32 v86, v10, v86, v83
	v_fmac_f32_e32 v85, v86, v84
	v_mul_f32_e32 v84, 0xbfb8aa3b, v82
	v_exp_f32_e32 v84, v84
	s_nop 0
	v_add_f32_e32 v84, 1.0, v84
	v_div_scale_f32 v86, s[2:3], v84, v84, v82
	v_rcp_f32_e32 v87, v86
	s_nop 0
	v_fma_f32 v88, -v86, v87, 1.0
	v_fmac_f32_e32 v87, v88, v87
	v_div_scale_f32 v88, vcc, v82, v84, v82
	v_mul_f32_e32 v89, v88, v87
	v_fma_f32 v90, -v86, v89, v88
	v_fmac_f32_e32 v89, v90, v87
	v_fma_f32 v86, -v86, v89, v88
	v_div_fmas_f32 v86, v86, v87, v89
	v_div_fixup_f32 v82, v86, v84, v82
	v_mul_f32_e32 v82, v82, v85
	v_cvt_pk_bf16_f32 v82, v82, s0
	ds_write_b16 v17, v82 offset:2560
	ds_write_b16 v17, v81 offset:2048
	v_add_f32_dpp v81, v80, v80 quad_perm:[1,0,3,2] row_mask:0xf bank_mask:0xf bound_ctrl:1
	v_mov_b32_e32 v82, v3
	s_waitcnt vmcnt(30)
	v_mov_b32_e32 v86, v39
	v_add_f32_dpp v81, v81, v81 quad_perm:[2,3,0,1] row_mask:0xf bank_mask:0xf bound_ctrl:1
	v_mov_b32_e32 v88, v37
	v_mov_b32_e32 v89, v34
	v_add_f32_dpp v81, v81, v81 row_ror:4 row_mask:0xf bank_mask:0xf bound_ctrl:1
	v_mov_b32_e32 v87, v22
	v_mov_b32_e32 v90, v30
	v_add_f32_dpp v81, v81, v81 row_ror:8 row_mask:0xf bank_mask:0xf bound_ctrl:1
	s_nop 1
	v_mov_b32_dpp v82, v81 row_bcast:15 row_mask:0xa bank_mask:0xf bound_ctrl:1
	v_add_f32_e32 v81, v81, v82
	v_mov_b32_e32 v82, v3
	s_nop 1
	v_mov_b32_dpp v82, v81 row_bcast:31 row_mask:0xc bank_mask:0xf bound_ctrl:1
	v_add_f32_e32 v81, v81, v82
	v_mov_b32_e32 v82, v3
	v_readlane_b32 s2, v81, 63
	s_nop 1
	v_fmac_f32_e32 v80, s2, v186
	v_mul_f32_e32 v81, v80, v80
	s_nop 1
	v_mov_b32_dpp v81, v81 quad_perm:[1,0,3,2] row_mask:0xf bank_mask:0xf bound_ctrl:1
	v_fmac_f32_e32 v81, v80, v80
	s_nop 1
	v_add_f32_dpp v81, v81, v81 quad_perm:[2,3,0,1] row_mask:0xf bank_mask:0xf bound_ctrl:1
	s_nop 1
	v_add_f32_dpp v81, v81, v81 row_ror:4 row_mask:0xf bank_mask:0xf bound_ctrl:1
	s_nop 1
	v_add_f32_dpp v81, v81, v81 row_ror:8 row_mask:0xf bank_mask:0xf bound_ctrl:1
	s_nop 1
	v_mov_b32_dpp v82, v81 row_bcast:15 row_mask:0xa bank_mask:0xf bound_ctrl:1
	v_add_f32_e32 v81, v81, v82
	v_mov_b32_e32 v82, v3
	s_nop 1
	v_mov_b32_dpp v82, v81 row_bcast:31 row_mask:0xc bank_mask:0xf bound_ctrl:1
	v_add_f32_e32 v81, v81, v82
	s_nop 0
	v_readlane_b32 s2, v81, 63
	s_nop 1
	v_fma_f32 v81, s2, v187, v182
	v_cmp_gt_f32_e32 vcc, s50, v81
	v_mul_f32_e32 v82, 0x4b800000, v81
	s_nop 0
	v_cndmask_b32_e32 v81, v81, v82, vcc
	v_rsq_f32_e32 v81, v81
	s_nop 0
	v_mul_f32_e32 v82, 0x45800000, v81
	v_cndmask_b32_e32 v81, v81, v82, vcc
	v_mul_f32_e32 v80, v80, v81
	v_sub_f32_e32 v81, v83, v78
	v_fma_f32 v80, v8, v80, v9
	v_fma_f32 v81, v10, v81, v78
	v_fmac_f32_e32 v80, v81, v79
	v_mul_f32_e32 v79, 0xbfb8aa3b, v77
	v_exp_f32_e32 v79, v79
	s_nop 0
	v_add_f32_e32 v79, 1.0, v79
	v_div_scale_f32 v81, s[2:3], v79, v79, v77
	v_rcp_f32_e32 v82, v81
	s_nop 0
	v_fma_f32 v83, -v81, v82, 1.0
	v_fmac_f32_e32 v82, v83, v82
	v_div_scale_f32 v83, vcc, v77, v79, v77
	v_mul_f32_e32 v84, v83, v82
	v_fma_f32 v85, -v81, v84, v83
	v_fmac_f32_e32 v84, v85, v82
	v_fma_f32 v81, -v81, v84, v83
	v_div_fmas_f32 v81, v81, v82, v84
	v_div_fixup_f32 v77, v81, v79, v77
	v_mul_f32_e32 v77, v77, v80
	v_cvt_pk_bf16_f32 v77, v77, s0
	ds_write_b16 v17, v77 offset:3584
	ds_write_b16 v17, v76 offset:3072
	v_add_f32_dpp v76, v75, v75 quad_perm:[1,0,3,2] row_mask:0xf bank_mask:0xf bound_ctrl:1
	v_mov_b32_e32 v77, v3
	s_waitcnt vmcnt(25)
	v_mov_b32_e32 v81, v44
	v_add_f32_dpp v76, v76, v76 quad_perm:[2,3,0,1] row_mask:0xf bank_mask:0xf bound_ctrl:1
	v_mov_b32_e32 v82, v42
	v_mov_b32_e32 v83, v40
	v_add_f32_dpp v76, v76, v76 row_ror:4 row_mask:0xf bank_mask:0xf bound_ctrl:1
	v_mov_b32_e32 v84, v35
	v_mov_b32_e32 v85, v32
	v_add_f32_dpp v76, v76, v76 row_ror:8 row_mask:0xf bank_mask:0xf bound_ctrl:1
	s_nop 1
	v_mov_b32_dpp v77, v76 row_bcast:15 row_mask:0xa bank_mask:0xf bound_ctrl:1
	v_add_f32_e32 v76, v76, v77
	v_mov_b32_e32 v77, v3
	s_nop 1
	v_mov_b32_dpp v77, v76 row_bcast:31 row_mask:0xc bank_mask:0xf bound_ctrl:1
	v_add_f32_e32 v76, v76, v77
	v_mov_b32_e32 v77, v3
	v_readlane_b32 s2, v76, 63
	s_nop 1
	v_fmac_f32_e32 v75, s2, v186
	v_mul_f32_e32 v76, v75, v75
	s_nop 1
	v_mov_b32_dpp v76, v76 quad_perm:[1,0,3,2] row_mask:0xf bank_mask:0xf bound_ctrl:1
	v_fmac_f32_e32 v76, v75, v75
	s_nop 1
	v_add_f32_dpp v76, v76, v76 quad_perm:[2,3,0,1] row_mask:0xf bank_mask:0xf bound_ctrl:1
	s_nop 1
	v_add_f32_dpp v76, v76, v76 row_ror:4 row_mask:0xf bank_mask:0xf bound_ctrl:1
	s_nop 1
	v_add_f32_dpp v76, v76, v76 row_ror:8 row_mask:0xf bank_mask:0xf bound_ctrl:1
	s_nop 1
	v_mov_b32_dpp v77, v76 row_bcast:15 row_mask:0xa bank_mask:0xf bound_ctrl:1
	v_add_f32_e32 v76, v76, v77
	v_mov_b32_e32 v77, v3
	s_nop 1
	v_mov_b32_dpp v77, v76 row_bcast:31 row_mask:0xc bank_mask:0xf bound_ctrl:1
	v_add_f32_e32 v76, v76, v77
	s_nop 0
	v_readlane_b32 s2, v76, 63
	s_nop 1
	v_fma_f32 v76, s2, v187, v182
	v_cmp_gt_f32_e32 vcc, s50, v76
	v_mul_f32_e32 v77, 0x4b800000, v76
	s_nop 0
	v_cndmask_b32_e32 v76, v76, v77, vcc
	v_rsq_f32_e32 v76, v76
	s_nop 0
	v_mul_f32_e32 v77, 0x45800000, v76
	v_cndmask_b32_e32 v76, v76, v77, vcc
	v_mul_f32_e32 v75, v75, v76
	v_sub_f32_e32 v76, v78, v73
	v_fma_f32 v75, v8, v75, v9
	v_fma_f32 v76, v10, v76, v73
	v_fmac_f32_e32 v75, v76, v74
	v_mul_f32_e32 v74, 0xbfb8aa3b, v72
	v_exp_f32_e32 v74, v74
	s_nop 0
	v_add_f32_e32 v74, 1.0, v74
	v_div_scale_f32 v76, s[2:3], v74, v74, v72
	v_rcp_f32_e32 v77, v76
	s_nop 0
	v_fma_f32 v78, -v76, v77, 1.0
	v_fmac_f32_e32 v77, v78, v77
	v_div_scale_f32 v78, vcc, v72, v74, v72
	v_mul_f32_e32 v79, v78, v77
	v_fma_f32 v80, -v76, v79, v78
	v_fmac_f32_e32 v79, v80, v77
	v_fma_f32 v76, -v76, v79, v78
	v_div_fmas_f32 v76, v76, v77, v79
	v_div_fixup_f32 v72, v76, v74, v72
	v_mul_f32_e32 v72, v72, v75
	v_cvt_pk_bf16_f32 v72, v72, s0
	ds_write_b16 v17, v72 offset:4608
	ds_write_b16 v17, v71 offset:4096
	v_add_f32_dpp v71, v65, v65 quad_perm:[1,0,3,2] row_mask:0xf bank_mask:0xf bound_ctrl:1
	v_mov_b32_e32 v72, v3
	s_waitcnt vmcnt(20)
	v_mov_b32_e32 v76, v50
	v_add_f32_dpp v71, v71, v71 quad_perm:[2,3,0,1] row_mask:0xf bank_mask:0xf bound_ctrl:1
	v_mov_b32_e32 v77, v47
	v_mov_b32_e32 v78, v45
	v_add_f32_dpp v71, v71, v71 row_ror:4 row_mask:0xf bank_mask:0xf bound_ctrl:1
	v_mov_b32_e32 v79, v41
	v_mov_b32_e32 v80, v38
	v_add_f32_dpp v71, v71, v71 row_ror:8 row_mask:0xf bank_mask:0xf bound_ctrl:1
	s_nop 1
	v_mov_b32_dpp v72, v71 row_bcast:15 row_mask:0xa bank_mask:0xf bound_ctrl:1
	v_add_f32_e32 v71, v71, v72
	v_mov_b32_e32 v72, v3
	s_nop 1
	v_mov_b32_dpp v72, v71 row_bcast:31 row_mask:0xc bank_mask:0xf bound_ctrl:1
	v_add_f32_e32 v71, v71, v72
	v_mov_b32_e32 v72, v3
	v_readlane_b32 s2, v71, 63
	s_nop 1
	v_fmac_f32_e32 v65, s2, v186
	v_mul_f32_e32 v71, v65, v65
	s_nop 1
	v_mov_b32_dpp v71, v71 quad_perm:[1,0,3,2] row_mask:0xf bank_mask:0xf bound_ctrl:1
	v_fmac_f32_e32 v71, v65, v65
	s_nop 1
	v_add_f32_dpp v71, v71, v71 quad_perm:[2,3,0,1] row_mask:0xf bank_mask:0xf bound_ctrl:1
	s_nop 1
	v_add_f32_dpp v71, v71, v71 row_ror:4 row_mask:0xf bank_mask:0xf bound_ctrl:1
	s_nop 1
	v_add_f32_dpp v71, v71, v71 row_ror:8 row_mask:0xf bank_mask:0xf bound_ctrl:1
	s_nop 1
	v_mov_b32_dpp v72, v71 row_bcast:15 row_mask:0xa bank_mask:0xf bound_ctrl:1
	v_add_f32_e32 v71, v71, v72
	v_mov_b32_e32 v72, v3
	s_nop 1
	v_mov_b32_dpp v72, v71 row_bcast:31 row_mask:0xc bank_mask:0xf bound_ctrl:1
	v_add_f32_e32 v71, v71, v72
	s_nop 0
	v_readlane_b32 s2, v71, 63
	s_nop 1
	v_fma_f32 v71, s2, v187, v182
	v_cmp_gt_f32_e32 vcc, s50, v71
	v_mul_f32_e32 v72, 0x4b800000, v71
	s_nop 0
	v_cndmask_b32_e32 v71, v71, v72, vcc
	v_rsq_f32_e32 v71, v71
	s_nop 0
	v_mul_f32_e32 v72, 0x45800000, v71
	v_cndmask_b32_e32 v71, v71, v72, vcc
	v_mul_f32_e32 v65, v65, v71
	v_sub_f32_e32 v71, v73, v57
	v_fma_f32 v65, v8, v65, v9
	v_fma_f32 v71, v10, v71, v57
	v_fmac_f32_e32 v65, v71, v60
	v_mul_f32_e32 v60, 0xbfb8aa3b, v48
	v_exp_f32_e32 v60, v60
	s_nop 0
	v_add_f32_e32 v60, 1.0, v60
	v_div_scale_f32 v71, s[2:3], v60, v60, v48
	v_rcp_f32_e32 v72, v71
	s_nop 0
	v_fma_f32 v73, -v71, v72, 1.0
	v_fmac_f32_e32 v72, v73, v72
	v_div_scale_f32 v73, vcc, v48, v60, v48
	v_mul_f32_e32 v74, v73, v72
	v_fma_f32 v75, -v71, v74, v73
	v_fmac_f32_e32 v74, v75, v72
	v_fma_f32 v71, -v71, v74, v73
	v_div_fmas_f32 v71, v71, v72, v74
	v_div_fixup_f32 v48, v71, v60, v48
	v_mul_f32_e32 v48, v48, v65
	v_cvt_pk_bf16_f32 v48, v48, s0
	ds_write_b16 v17, v48 offset:5632
	ds_write_b16 v17, v36 offset:5120
	v_add_f32_dpp v36, v27, v27 quad_perm:[1,0,3,2] row_mask:0xf bank_mask:0xf bound_ctrl:1
	v_mov_b32_e32 v48, v3
	s_waitcnt vmcnt(15)
	v_mov_b32_e32 v71, v55
	v_add_f32_dpp v36, v36, v36 quad_perm:[2,3,0,1] row_mask:0xf bank_mask:0xf bound_ctrl:1
	v_mov_b32_e32 v72, v53
	v_mov_b32_e32 v73, v51
	v_add_f32_dpp v36, v36, v36 row_ror:4 row_mask:0xf bank_mask:0xf bound_ctrl:1
	v_mov_b32_e32 v74, v46
	v_mov_b32_e32 v75, v43
	v_add_f32_dpp v36, v36, v36 row_ror:8 row_mask:0xf bank_mask:0xf bound_ctrl:1
	s_nop 1
	v_mov_b32_dpp v48, v36 row_bcast:15 row_mask:0xa bank_mask:0xf bound_ctrl:1
	v_add_f32_e32 v36, v36, v48
	v_mov_b32_e32 v48, v3
	s_nop 1
	v_mov_b32_dpp v48, v36 row_bcast:31 row_mask:0xc bank_mask:0xf bound_ctrl:1
	v_add_f32_e32 v36, v36, v48
	v_mov_b32_e32 v48, v3
	v_readlane_b32 s2, v36, 63
	s_nop 1
	v_fmac_f32_e32 v27, s2, v186
	v_mul_f32_e32 v36, v27, v27
	s_nop 1
	v_mov_b32_dpp v36, v36 quad_perm:[1,0,3,2] row_mask:0xf bank_mask:0xf bound_ctrl:1
	v_fmac_f32_e32 v36, v27, v27
	s_nop 1
	v_add_f32_dpp v36, v36, v36 quad_perm:[2,3,0,1] row_mask:0xf bank_mask:0xf bound_ctrl:1
	s_nop 1
	v_add_f32_dpp v36, v36, v36 row_ror:4 row_mask:0xf bank_mask:0xf bound_ctrl:1
	s_nop 1
	v_add_f32_dpp v36, v36, v36 row_ror:8 row_mask:0xf bank_mask:0xf bound_ctrl:1
	s_nop 1
	v_mov_b32_dpp v48, v36 row_bcast:15 row_mask:0xa bank_mask:0xf bound_ctrl:1
	v_add_f32_e32 v36, v36, v48
	v_mov_b32_e32 v48, v3
	s_nop 1
	v_mov_b32_dpp v48, v36 row_bcast:31 row_mask:0xc bank_mask:0xf bound_ctrl:1
	v_add_f32_e32 v36, v36, v48
	s_nop 0
	v_readlane_b32 s2, v36, 63
	s_nop 1
	v_fma_f32 v36, s2, v187, v182
	v_cmp_gt_f32_e32 vcc, s50, v36
	v_mul_f32_e32 v48, 0x4b800000, v36
	s_nop 0
	v_cndmask_b32_e32 v36, v36, v48, vcc
	v_rsq_f32_e32 v36, v36
	s_nop 0
	v_mul_f32_e32 v48, 0x45800000, v36
	v_cndmask_b32_e32 v36, v36, v48, vcc
	v_mul_f32_e32 v27, v27, v36
	v_sub_f32_e32 v36, v57, v23
	v_fma_f32 v27, v8, v27, v9
	v_fma_f32 v36, v10, v36, v23
	v_fmac_f32_e32 v27, v36, v24
	v_mul_f32_e32 v24, 0xbfb8aa3b, v21
	v_exp_f32_e32 v24, v24
	s_nop 0
	v_add_f32_e32 v24, 1.0, v24
	v_div_scale_f32 v36, s[2:3], v24, v24, v21
	v_rcp_f32_e32 v48, v36
	s_nop 0
	v_fma_f32 v57, -v36, v48, 1.0
	v_fmac_f32_e32 v48, v57, v48
	v_div_scale_f32 v57, vcc, v21, v24, v21
	v_mul_f32_e32 v60, v57, v48
	v_fma_f32 v65, -v36, v60, v57
	v_fmac_f32_e32 v60, v65, v48
	v_fma_f32 v36, -v36, v60, v57
	v_div_fmas_f32 v36, v36, v48, v60
	v_div_fixup_f32 v21, v36, v24, v21
	v_mul_f32_e32 v21, v21, v27
	v_cvt_pk_bf16_f32 v21, v21, s0
	ds_write_b16 v17, v21 offset:6656
	ds_write_b16 v17, v20 offset:6144
	v_add_f32_dpp v20, v16, v16 quad_perm:[1,0,3,2] row_mask:0xf bank_mask:0xf bound_ctrl:1
	v_mov_b32_e32 v21, v3
	s_waitcnt vmcnt(10)
	v_mov_b32_e32 v36, v62
	v_add_f32_dpp v20, v20, v20 quad_perm:[2,3,0,1] row_mask:0xf bank_mask:0xf bound_ctrl:1
	v_mov_b32_e32 v48, v59
	v_mov_b32_e32 v57, v56
	v_add_f32_dpp v20, v20, v20 row_ror:4 row_mask:0xf bank_mask:0xf bound_ctrl:1
	v_mov_b32_e32 v60, v52
	s_waitcnt vmcnt(9)
	v_mov_b32_e32 v27, v54
	v_add_f32_dpp v20, v20, v20 row_ror:8 row_mask:0xf bank_mask:0xf bound_ctrl:1
	v_mov_b32_e32 v65, v49
	s_nop 0
	v_mov_b32_dpp v21, v20 row_bcast:15 row_mask:0xa bank_mask:0xf bound_ctrl:1
	v_add_f32_e32 v20, v20, v21
	v_mov_b32_e32 v21, v3
	s_nop 1
	v_mov_b32_dpp v21, v20 row_bcast:31 row_mask:0xc bank_mask:0xf bound_ctrl:1
	v_add_f32_e32 v20, v20, v21
	v_mov_b32_e32 v21, v3
	v_readlane_b32 s2, v20, 63
	s_nop 1
	v_fmac_f32_e32 v16, s2, v186
	v_mul_f32_e32 v20, v16, v16
	s_nop 1
	v_mov_b32_dpp v20, v20 quad_perm:[1,0,3,2] row_mask:0xf bank_mask:0xf bound_ctrl:1
	v_fmac_f32_e32 v20, v16, v16
	s_nop 1
	v_add_f32_dpp v20, v20, v20 quad_perm:[2,3,0,1] row_mask:0xf bank_mask:0xf bound_ctrl:1
	s_nop 1
	v_add_f32_dpp v20, v20, v20 row_ror:4 row_mask:0xf bank_mask:0xf bound_ctrl:1
	s_nop 1
	v_add_f32_dpp v20, v20, v20 row_ror:8 row_mask:0xf bank_mask:0xf bound_ctrl:1
	s_nop 1
	v_mov_b32_dpp v21, v20 row_bcast:15 row_mask:0xa bank_mask:0xf bound_ctrl:1
	v_add_f32_e32 v20, v20, v21
	v_mov_b32_e32 v21, v3
	s_nop 1
	v_mov_b32_dpp v21, v20 row_bcast:31 row_mask:0xc bank_mask:0xf bound_ctrl:1
	v_add_f32_e32 v20, v20, v21
	s_nop 0
	v_readlane_b32 s2, v20, 63
	s_nop 1
	v_fma_f32 v20, s2, v187, v182
	v_cmp_gt_f32_e32 vcc, s50, v20
	v_mul_f32_e32 v21, 0x4b800000, v20
	s_nop 0
	v_cndmask_b32_e32 v20, v20, v21, vcc
	v_rsq_f32_e32 v20, v20
	s_nop 0
	v_mul_f32_e32 v21, 0x45800000, v20
	v_cndmask_b32_e32 v20, v20, v21, vcc
	v_mul_f32_e32 v16, v16, v20
	v_sub_f32_e32 v20, v23, v14
	v_fma_f32 v16, v8, v16, v9
	v_fmac_f32_e32 v14, v10, v20
	v_fmac_f32_e32 v16, v14, v15
	v_mul_f32_e32 v14, 0xbfb8aa3b, v13
	v_exp_f32_e32 v14, v14
	s_nop 0
	v_add_f32_e32 v14, 1.0, v14
	v_div_scale_f32 v15, s[2:3], v14, v14, v13
	v_rcp_f32_e32 v20, v15
	s_nop 0
	v_fma_f32 v21, -v15, v20, 1.0
	v_fmac_f32_e32 v20, v21, v20
	v_div_scale_f32 v21, vcc, v13, v14, v13
	v_mul_f32_e32 v23, v21, v20
	v_fma_f32 v24, -v15, v23, v21
	v_fmac_f32_e32 v23, v24, v20
	v_fma_f32 v15, -v15, v23, v21
	v_div_fmas_f32 v15, v15, v20, v23
	v_div_fixup_f32 v13, v15, v14, v13
	v_mul_f32_e32 v13, v13, v16
	v_cvt_pk_bf16_f32 v13, v13, s0
	ds_write_b16 v17, v13 offset:7680
	ds_write_b16 v17, v12 offset:7168
	s_waitcnt lgkmcnt(0)
	s_barrier
	ds_read_b128 v[12:15], v19
	v_add_u32_e32 v20, s20, v11
	v_ashrrev_i32_e32 v21, 31, v20
	v_lshlrev_b64 v[20:21], 11, v[20:21]
	v_lshl_add_u64 v[20:21], v[6:7], 0, v[20:21]
	s_waitcnt lgkmcnt(0)
	s_waitcnt vmcnt(0)
	global_store_dwordx4 v[20:21], v[12:15], off offset:1024
	ds_read_b128 v[12:15], v2
	v_add_u32_e32 v20, s20, v18
	v_ashrrev_i32_e32 v21, 31, v20
	v_lshlrev_b64 v[20:21], 11, v[20:21]
	v_lshl_add_u64 v[20:21], v[6:7], 0, v[20:21]
	s_waitcnt lgkmcnt(0)
	global_store_dwordx4 v[20:21], v[12:15], off offset:1024
	s_and_b64 vcc, exec, s[0:1]
	s_mov_b32 s20, s39
	v_mov_b32_e32 v12, v70
	v_mov_b32_e32 v20, v67
	v_mov_b32_e32 v13, v69
	v_mov_b32_e32 v21, v66
	v_mov_b32_e32 v14, v68
	v_mov_b32_e32 v23, v63
	v_mov_b32_e32 v15, v64
	v_mov_b32_e32 v24, v58
	v_mov_b32_e32 v16, v61
	s_barrier
	s_cbranch_vccnz .LBB0_42
